# speedup vs baseline: 1.1285x; 1.0046x over previous
; __device__ __forceinline__ void hgrn_phase(const Params& P, char* shm, int lbid) {
;     ...
;     f32x4 Sacc[8];
; #pragma unroll
;     for (int vt = 0; vt < 8; ++vt) Sacc[vt] = f32x4{0.f, 0.f, 0.f, 0.f};
;     char* sb = shm + SB0;
;     HG_ISSUE(0);
;     HG_PRODUCE(0);
;     HG_ISSUE(1);
;     for (int c = 0; c < NCH; ++c) {
.LBB0_907:
	s_or_b64 exec, exec, s[0:1]
	v_lshlrev_b32_e32 v107, 1, v15
	s_movk_i32 s0, 0x50
	v_mad_u32_u24 v4, v16, s0, v107
	v_readlane_b32 s0, v254, 7
	s_waitcnt vmcnt(0)
	ds_write_b16 v4, v0 offset:27648
	ds_write_b16_d16_hi v4, v0 offset:27728
	ds_write_b16 v4, v1 offset:27808
	ds_write_b16_d16_hi v4, v1 offset:27888
	ds_write_b16 v4, v2 offset:27968
	ds_write_b16_d16_hi v4, v2 offset:28048
	ds_write_b16 v4, v3 offset:28128
	ds_write_b16_d16_hi v4, v3 offset:28208
	v_add_u32_e32 v0, s0, v114
	v_mul_u32_u24_e32 v106, 0x50, v16
	v_ashrrev_i32_e32 v1, 31, v0
	v_add_u32_e32 v4, s0, v94
	v_add_u32_e32 v8, s0, v95
	v_add_u32_e32 v16, s0, v96
	v_lshlrev_b64 v[0:1], 9, v[0:1]
	v_ashrrev_i32_e32 v5, 31, v4
	v_ashrrev_i32_e32 v9, 31, v8
	s_waitcnt lgkmcnt(14)
	v_ashrrev_i32_e32 v17, 31, v16
	v_lshl_add_u64 v[0:1], v[0:1], 0, v[72:73]
	v_lshlrev_b64 v[4:5], 9, v[4:5]
	v_lshlrev_b64 v[8:9], 9, v[8:9]
	v_lshlrev_b64 v[16:17], 9, v[16:17]
	v_lshl_add_u64 v[2:3], v[0:1], 2, s[34:35]
	v_lshl_add_u64 v[0:1], v[0:1], 1, s[62:63]
	v_lshl_add_u64 v[4:5], v[4:5], 0, v[72:73]
	v_lshl_add_u64 v[8:9], v[8:9], 0, v[72:73]
	v_lshl_add_u64 v[16:17], v[16:17], 0, v[72:73]
	v_lshl_add_u64 v[6:7], v[4:5], 2, s[34:35]
	v_lshl_add_u64 v[4:5], v[4:5], 1, s[62:63]
	v_lshl_add_u64 v[10:11], v[8:9], 2, s[34:35]
	v_lshl_add_u64 v[8:9], v[8:9], 1, s[62:63]
	v_lshl_add_u64 v[18:19], v[16:17], 2, s[34:35]
	v_lshl_add_u64 v[16:17], v[16:17], 1, s[62:63]
	global_load_dword v84, v[2:3], off
	global_load_ushort v125, v[0:1], off
	global_load_dword v85, v[6:7], off
	global_load_ushort v124, v[4:5], off
	global_load_dword v78, v[10:11], off
	global_load_ushort v123, v[8:9], off
	global_load_dword v79, v[18:19], off
	global_load_ushort v121, v[16:17], off
	v_add_u32_e32 v0, s0, v97
	v_ashrrev_i32_e32 v1, 31, v0
	v_add_u32_e32 v4, s0, v99
	v_add_u32_e32 v8, s0, v101
	v_add_u32_e32 v16, s0, v103
	v_lshlrev_b64 v[0:1], 9, v[0:1]
	v_ashrrev_i32_e32 v5, 31, v4
	v_ashrrev_i32_e32 v9, 31, v8
	v_ashrrev_i32_e32 v17, 31, v16
	v_lshl_add_u64 v[0:1], v[0:1], 0, v[72:73]
	v_lshlrev_b64 v[4:5], 9, v[4:5]
	v_lshlrev_b64 v[8:9], 9, v[8:9]
	v_lshlrev_b64 v[16:17], 9, v[16:17]
	v_lshl_add_u64 v[2:3], v[0:1], 2, s[34:35]
	v_lshl_add_u64 v[4:5], v[4:5], 0, v[72:73]
	v_lshl_add_u64 v[8:9], v[8:9], 0, v[72:73]
	v_lshl_add_u64 v[16:17], v[16:17], 0, v[72:73]
	v_lshl_add_u64 v[0:1], v[0:1], 1, s[62:63]
	v_lshl_add_u64 v[6:7], v[4:5], 2, s[34:35]
	v_lshl_add_u64 v[4:5], v[4:5], 1, s[62:63]
	v_lshl_add_u64 v[10:11], v[8:9], 2, s[34:35]
	v_lshl_add_u64 v[8:9], v[8:9], 1, s[62:63]
	v_lshl_add_u64 v[18:19], v[16:17], 2, s[34:35]
	v_lshl_add_u64 v[16:17], v[16:17], 1, s[62:63]
	global_load_dword v82, v[2:3], off
	global_load_ushort v122, v[0:1], off
	global_load_dword v83, v[6:7], off
	global_load_ushort v120, v[4:5], off
	global_load_dword v76, v[10:11], off
	global_load_ushort v119, v[8:9], off
	global_load_dword v77, v[18:19], off
	global_load_ushort v118, v[16:17], off
	v_add_u32_e32 v0, s0, v105
	v_ashrrev_i32_e32 v1, 31, v0
	v_readlane_b32 s0, v254, 4
	v_lshlrev_b64 v[0:1], 10, v[0:1]
	v_readlane_b32 s1, v254, 5
	v_lshlrev_b32_e32 v6, 2, v93
	v_or_b32_e32 v7, v6, v13
	v_lshl_add_u64 v[0:1], s[0:1], 0, v[0:1]
	v_lshl_add_u64 v[0:1], v[0:1], 0, v[224:225]
	global_load_dwordx4 v[0:3], v[0:1], off
	v_lshlrev_b32_e32 v113, 2, v7
	v_and_b32_e32 v7, -16, v15
	v_lshl_add_u64 v[80:81], s[0:1], 0, v[224:225]
	v_or_b32_e32 v8, v7, v12
	s_movk_i32 s0, 0x110
	v_or_b32_e32 v10, 2, v6
	v_lshlrev_b32_e32 v4, 5, v14
	v_mul_lo_u32 v112, v8, s0
	v_cmp_gt_i32_e64 s[18:19], v10, v8
	v_or_b32_e32 v10, 3, v6
	s_movk_i32 s0, 0x60
	v_or_b32_e32 v7, v6, v7
	v_cmp_gt_i32_e64 s[20:21], v10, v8
	v_or_b32_e32 v10, 16, v6
	v_and_or_b32 v68, v4, s0, v12
	v_readlane_b32 s0, v251, 17
	v_cmp_gt_i32_e64 s[6:7], v10, v8
	v_or_b32_e32 v10, 17, v6
	v_mul_lo_u32 v89, v7, s0
	v_or_b32_e32 v5, v4, v69
	v_cmp_gt_i32_e64 s[16:17], v6, v8
	v_cmp_lt_i32_e64 s[14:15], v6, v8
	v_cmp_gt_i32_e64 s[8:9], v10, v8
	v_or_b32_e32 v10, 18, v6
	v_or_b32_e32 v6, 19, v6
	v_readlane_b32 s4, v254, 11
	v_add_u32_e32 v88, s0, v89
	v_add_u32_e32 v5, 0x12c00, v5
	v_or_b32_e32 v9, 0x12c00, v92
	v_mul_u32_u24_e32 v100, 0x110, v12
	v_cmp_gt_i32_e64 s[12:13], v6, v8
	v_mul_u32_u24_e32 v6, 0x110, v68
	v_lshlrev_b32_e32 v224, 2, v68
	v_readlane_b32 s5, v254, 12
	v_add_u32_e32 v87, s0, v88
	v_mov_b32_e32 v4, 0
	v_mul_u32_u24_e32 v116, 0x880, v93
	v_mul_u32_u24_e32 v115, 0x110, v32
	v_lshlrev_b32_e32 v108, 2, v31
	v_mul_u32_u24_e32 v117, 0x50, v12
	v_cmp_gt_i32_e64 s[10:11], v10, v8
	v_mul_u32_u24_e32 v90, 0x50, v68
	v_lshl_add_u64 v[70:71], s[4:5], 0, v[224:225]
	v_add_u32_e32 v86, s0, v87
	s_mov_b32 s50, 0
	s_movk_i32 s51, 0x8ff
	v_add_u32_e32 v91, v5, v100
	v_add_u32_e32 v75, v9, v6
	s_mov_b32 s61, 0
	v_mov_b32_e32 v5, v4
	v_mov_b32_e32 v6, v4
	v_mov_b32_e32 v7, v4
	v_mov_b32_e32 v36, v4
	v_mov_b32_e32 v37, v4
	v_mov_b32_e32 v38, v4
	v_mov_b32_e32 v39, v4
	v_mov_b32_e32 v12, v4
	v_mov_b32_e32 v13, v4
	v_mov_b32_e32 v14, v4
	v_mov_b32_e32 v15, v4
	v_mov_b32_e32 v40, v4
	v_mov_b32_e32 v41, v4
	v_mov_b32_e32 v42, v4
	v_mov_b32_e32 v43, v4
	v_mov_b32_e32 v16, v4
	v_mov_b32_e32 v17, v4
	v_mov_b32_e32 v18, v4
	v_mov_b32_e32 v19, v4
	v_mov_b32_e32 v44, v4
	v_mov_b32_e32 v45, v4
	v_mov_b32_e32 v46, v4
	v_mov_b32_e32 v47, v4
	v_mov_b32_e32 v20, v4
	v_mov_b32_e32 v21, v4
	v_mov_b32_e32 v22, v4
	v_mov_b32_e32 v23, v4
	v_mov_b32_e32 v48, v4
	v_mov_b32_e32 v49, v4
	v_mov_b32_e32 v50, v4
	v_mov_b32_e32 v51, v4
	v_mov_b32_e32 v24, v4
	v_mov_b32_e32 v25, v4
	v_mov_b32_e32 v26, v4
	v_mov_b32_e32 v27, v4
	v_mov_b32_e32 v52, v4
	v_mov_b32_e32 v53, v4
	v_mov_b32_e32 v54, v4
	v_mov_b32_e32 v55, v4
	v_mov_b32_e32 v28, v4
	v_mov_b32_e32 v29, v4
	v_mov_b32_e32 v30, v4
	v_mov_b32_e32 v31, v4
	v_mov_b32_e32 v56, v4
	v_mov_b32_e32 v57, v4
	v_mov_b32_e32 v58, v4
	v_mov_b32_e32 v59, v4
	v_mov_b32_e32 v32, v4
	v_mov_b32_e32 v33, v4
	v_mov_b32_e32 v34, v4
	v_mov_b32_e32 v35, v4
	v_mov_b32_e32 v60, v4
	v_mov_b32_e32 v61, v4
	v_mov_b32_e32 v62, v4
	v_mov_b32_e32 v63, v4
	v_mov_b32_e32 v8, v4
	v_mov_b32_e32 v9, v4
	v_mov_b32_e32 v10, v4
	v_mov_b32_e32 v11, v4
	v_mov_b32_e32 v64, v4
	v_mov_b32_e32 v65, v4
	v_mov_b32_e32 v66, v4
	v_mov_b32_e32 v67, v4
	s_waitcnt vmcnt(0)
; __device__ __forceinline__ void hgrn_phase(const Params& P, char* shm, int lbid) {
;     ...
; #pragma unroll
;       for (int vt = 0; vt < 8; ++vt) {
;         u32x2 pk;
;         pk.x = pack2(Sacc[vt][0], Sacc[vt][1]);
;         pk.y = pack2(Sacc[vt][2], Sacc[vt][3]);
;         *(u32x2*)(sb + (vt * 16 + fr) * QSTR + (16 * w + quad * 4) * 2) = pk;
;       }
.LBB0_908:
	v_cvt_pk_bf16_f32 v4, v4, v5
	v_cvt_pk_bf16_f32 v5, v6, v7
	ds_write_b64 v91, v[4:5]
	v_cvt_pk_bf16_f32 v4, v12, v13
	v_cvt_pk_bf16_f32 v5, v14, v15
	ds_write_b64 v91, v[4:5] offset:4352
	v_cvt_pk_bf16_f32 v5, v18, v19
	v_mul_f32_e32 v18, v84, v85
	v_cvt_pk_bf16_f32 v4, v16, v17
	v_mul_f32_e32 v17, v78, v18
	v_mul_f32_e32 v16, v79, v17
	ds_write_b64 v91, v[4:5] offset:8704
	v_cvt_pk_bf16_f32 v4, v20, v21
	v_cvt_pk_bf16_f32 v5, v22, v23
	v_mul_f32_e32 v15, v82, v16
	ds_write_b64 v91, v[4:5] offset:13056
	v_cvt_pk_bf16_f32 v4, v24, v25
	v_cvt_pk_bf16_f32 v5, v26, v27
	v_mul_f32_e32 v14, v83, v15
	ds_write_b64 v91, v[4:5] offset:17408
	v_cvt_pk_bf16_f32 v4, v28, v29
	v_cvt_pk_bf16_f32 v5, v30, v31
	v_mul_f32_e32 v13, v76, v14
	ds_write_b64 v91, v[4:5] offset:21760
	v_cvt_pk_bf16_f32 v4, v32, v33
	v_cvt_pk_bf16_f32 v5, v34, v35
	v_mul_f32_e32 v12, v77, v13
	ds_write_b64 v91, v[4:5] offset:26112
	ds_bpermute_b32 v4, v102, v12
	ds_bpermute_b32 v5, v109, v12
	ds_bpermute_b32 v6, v110, v12
	ds_bpermute_b32 v7, v111, v12
	v_cvt_pk_bf16_f32 v8, v8, v9
	v_cvt_pk_bf16_f32 v9, v10, v11
	ds_write_b64 v91, v[8:9] offset:30464
	v_mov_b32_e32 v8, 1.0
	s_and_saveexec_b64 s[0:1], s[24:25]
	s_cbranch_execz .LBB0_916
	v_cmp_lt_i32_e32 vcc, 1, v93
	s_waitcnt lgkmcnt(4)
	v_mov_b32_e32 v8, v4
	s_and_saveexec_b64 s[4:5], vcc
	s_cbranch_execz .LBB0_915
	s_mov_b64 s[26:27], s[90:91]
	v_cmp_ne_u32_e32 vcc, 2, v93
	s_and_saveexec_b64 s[58:59], vcc
	s_xor_b64 vcc, exec, s[58:59]
	s_cbranch_execz .LBB0_912
	s_waitcnt lgkmcnt(3)
	v_mul_f32_e32 v8, v4, v5
	s_waitcnt lgkmcnt(2)
	v_mul_f32_e32 v8, v8, v6

.LBB0_916:
	s_or_b64 exec, exec, s[0:1]
	s_add_i32 s4, s61, 1
	s_bitcmp1_b32 s4, 0
	s_cselect_b32 s5, 0x9600, 0
	v_mul_f32_e32 v19, v84, v8
	v_lshlrev_b32_e32 v10, 16, v125
	v_add_u32_e32 v9, s5, v98
	v_mul_f32_e32 v21, v19, v10
	v_max_f32_e32 v19, 0xda24260, v19
	v_rcp_f32_e32 v20, v19
	v_cvt_pk_bf16_f32 v19, v21, s0
	v_add_u32_e32 v22, v9, v116
	ds_write_b16 v22, v19
	v_mul_f32_e32 v18, v18, v8
	v_lshlrev_b32_e32 v19, 16, v124
	v_mul_f32_e32 v19, v18, v19
	v_max_f32_e32 v18, 0xda24260, v18
	v_rcp_f32_e32 v21, v18
	v_pk_add_f32 v[10:11], v[84:85], 1.0 op_sel_hi:[1,0] neg_lo:[1,0] neg_hi:[1,0]
	v_add_u32_e32 v9, v9, v115
	v_mul_f32_e32 v17, v17, v8
	v_pk_mul_f32 v[10:11], v[10:11], v[20:21]
	v_mul_f32_e32 v16, v16, v8
	v_cvt_pk_bf16_f32 v18, v10, s0
	ds_write_b16 v22, v18 offset:8704
	v_cvt_pk_bf16_f32 v18, v19, s0
	ds_write_b16 v9, v18
	v_cvt_pk_bf16_f32 v18, v11, s0
	ds_write_b16 v9, v18 offset:8704
	v_lshlrev_b32_e32 v18, 16, v123
	v_mul_f32_e32 v21, v17, v18
	v_max_f32_e32 v17, 0xda24260, v17
	v_rcp_f32_e32 v20, v17
	v_cvt_pk_bf16_f32 v17, v21, s0
	ds_write_b16 v9, v17 offset:272
	v_lshlrev_b32_e32 v17, 16, v121
	v_mul_f32_e32 v22, v16, v17
	v_max_f32_e32 v16, 0xda24260, v16
	v_rcp_f32_e32 v21, v16
	v_pk_add_f32 v[18:19], v[78:79], 1.0 op_sel_hi:[1,0] neg_lo:[1,0] neg_hi:[1,0]
	v_mul_f32_e32 v15, v15, v8
	v_mul_f32_e32 v14, v14, v8
	v_pk_mul_f32 v[16:17], v[18:19], v[20:21]
	v_mul_f32_e32 v13, v13, v8
	v_cvt_pk_bf16_f32 v18, v16, s0
	ds_write_b16 v9, v18 offset:8976
	v_cvt_pk_bf16_f32 v18, v22, s0
	ds_write_b16 v9, v18 offset:544
	v_cvt_pk_bf16_f32 v18, v17, s0
	ds_write_b16 v9, v18 offset:9248
	v_lshlrev_b32_e32 v18, 16, v122
	v_mul_f32_e32 v21, v15, v18
	v_max_f32_e32 v15, 0xda24260, v15
	v_rcp_f32_e32 v20, v15
	v_cvt_pk_bf16_f32 v15, v21, s0
	ds_write_b16 v9, v15 offset:816
	v_lshlrev_b32_e32 v15, 16, v120
	v_mul_f32_e32 v22, v14, v15
	v_max_f32_e32 v14, 0xda24260, v14
	v_rcp_f32_e32 v21, v14
	v_pk_add_f32 v[18:19], v[82:83], 1.0 op_sel_hi:[1,0] neg_lo:[1,0] neg_hi:[1,0]
	v_mul_f32_e32 v8, v12, v8
	v_lshlrev_b32_e32 v12, 16, v118
	v_pk_mul_f32 v[14:15], v[18:19], v[20:21]
	s_nop 0
	v_cvt_pk_bf16_f32 v18, v14, s0
	ds_write_b16 v9, v18 offset:9520
	v_cvt_pk_bf16_f32 v18, v22, s0
	ds_write_b16 v9, v18 offset:1088
	v_cvt_pk_bf16_f32 v18, v15, s0
	ds_write_b16 v9, v18 offset:9792
	v_lshlrev_b32_e32 v18, 16, v119
	v_mul_f32_e32 v21, v13, v18
	v_max_f32_e32 v13, 0xda24260, v13
	v_mul_f32_e32 v22, v8, v12
	v_max_f32_e32 v8, 0xda24260, v8
	v_rcp_f32_e32 v20, v13
	v_cvt_pk_bf16_f32 v13, v21, s0
	v_rcp_f32_e32 v21, v8
	v_pk_add_f32 v[18:19], v[76:77], 1.0 op_sel_hi:[1,0] neg_lo:[1,0] neg_hi:[1,0]
	ds_write_b16 v9, v13 offset:1360
	v_pk_mul_f32 v[12:13], v[18:19], v[20:21]
	s_nop 0
	v_cvt_pk_bf16_f32 v8, v12, s0
	ds_write_b16 v9, v8 offset:10064
	v_cvt_pk_bf16_f32 v8, v22, s0
	ds_write_b16 v9, v8 offset:1632
	v_cvt_pk_bf16_f32 v8, v13, s0
	ds_write_b16 v9, v8 offset:10336
	v_cvt_pk_bf16_f32 v8, v10, v11
	v_cvt_pk_bf16_f32 v9, v16, v17
	v_cvt_pk_bf16_f32 v10, v14, v15
	v_cvt_pk_bf16_f32 v11, v12, v13
	v_add3_u32 v12, s5, v74, v92
	ds_write_b128 v12, v[8:11] offset:17408
	s_and_saveexec_b64 s[0:1], s[22:23]
	s_cbranch_execz .LBB0_918
	s_waitcnt lgkmcnt(14)
	v_mul_f32_e32 v4, v4, v5
	v_mul_f32_e32 v4, v4, v6
	v_mul_f32_e32 v4, v4, v7
	v_add_u32_e32 v5, s5, v108
	ds_write_b32 v5, v4 offset:37888
.LBB0_918:
	s_or_b64 exec, exec, s[0:1]
	s_waitcnt lgkmcnt(14)
	v_add3_u32 v4, s5, v106, v107
	s_cmp_gt_u32 s61, 5
	s_mov_b64 s[0:1], -1
	s_waitcnt vmcnt(8)
	ds_write_b16 v4, v0 offset:27648
	ds_write_b16_d16_hi v4, v0 offset:27728
	ds_write_b16 v4, v1 offset:27808
	ds_write_b16_d16_hi v4, v1 offset:27888
	ds_write_b16 v4, v2 offset:27968
	ds_write_b16_d16_hi v4, v2 offset:28048
	ds_write_b16 v4, v3 offset:28128
	ds_write_b16_d16_hi v4, v3 offset:28208
	s_cbranch_scc0 .LBB0_920
	v_readlane_b32 s0, v251, 15
	s_sub_i32 s5, s51, 64
	s_add_i32 s58, s50, 0xffffff40
	v_readlane_b32 s1, v251, 16
	s_and_b64 s[0:1], s[0:1], exec
	s_cselect_b32 s0, s58, s5
	v_readlane_b32 s1, v254, 36
	s_add_i32 s5, s0, s1
	s_mov_b64 s[0:1], 0

; __device__ __forceinline__ void hgrn_phase(const Params& P, char* shm, int lbid) {
;     ...
;       __syncthreads();
;       const char* pb = shm + (c & 1) * PB;
;       {
;         const bf16x8 a = *(const bf16x8*)(pb + PB_KT + (16 * w + fr) * TSTR + quad * 16);
;         const float4 gl = *(const float4*)(pb + PB_GL + (16 * w + quad * 4) * 4);
; #pragma unroll
;         for (int vt = 0; vt < 8; ++vt) {
;           const bf16x8 bv = *(const bf16x8*)(pb + PB_VT + (vt * 16 + fr) * TSTR + quad * 16);
;           f32x4 t = __builtin_amdgcn_mfma_f32_16x16x32_bf16(a, bv, Sacc[vt], 0, 0, 0);
;           t[0] *= gl.x; t[1] *= gl.y; t[2] *= gl.z; t[3] *= gl.w;
;           Sacc[vt] = t;
;         }
;       }
;       {
;         const int tt = w >> 2, vt0 = (w & 3) * 2;
;         bf16x8 qf[4];
; #pragma unroll
;         for (int ks = 0; ks < 4; ++ks) qf[ks] = *(const bf16x8*)(pb + PB_Q + (tt * 16 + fr) * QSTR + (ks * 32 + quad * 8) * 2);
;         f32x4 AT[2];
; #pragma unroll
;         for (int st = 0; st < 2; ++st) {
;           f32x4 acc = f32x4{0.f, 0.f, 0.f, 0.f};
; #pragma unroll
;           for (int ks = 0; ks < 4; ++ks) {
;             const bf16x8 kf = *(const bf16x8*)(pb + PB_K + (st * 16 + fr) * QSTR + (ks * 32 + quad * 8) * 2);
;             acc = __builtin_amdgcn_mfma_f32_16x16x32_bf16(kf, qf[ks], acc, 0, 0, 0);
;           }
;           const int tpos = tt * 16 + fr;
; #pragma unroll
;           for (int jj = 0; jj < 4; ++jj)
;             if (st * 16 + quad * 4 + jj > tpos) acc[jj] = 0.0f;
;           AT[st] = acc;
;         }
.LBB0_922:
	v_add_u32_e32 v0, s5, v114
	v_ashrrev_i32_e32 v1, 31, v0
	v_lshlrev_b64 v[0:1], 9, v[0:1]
	v_lshl_add_u64 v[0:1], v[0:1], 0, v[72:73]
	v_lshl_add_u64 v[2:3], v[0:1], 2, s[34:35]
	v_lshl_add_u64 v[0:1], v[0:1], 1, s[62:63]
	global_load_dword v84, v[2:3], off
	global_load_ushort v206, v[0:1], off
	v_add_u32_e32 v0, s5, v94
	v_ashrrev_i32_e32 v1, 31, v0
	v_lshlrev_b64 v[0:1], 9, v[0:1]
	v_lshl_add_u64 v[0:1], v[0:1], 0, v[72:73]
	v_lshl_add_u64 v[2:3], v[0:1], 2, s[34:35]
	v_lshl_add_u64 v[0:1], v[0:1], 1, s[62:63]
	global_load_dword v85, v[2:3], off
	global_load_ushort v207, v[0:1], off
	v_add_u32_e32 v0, s5, v95
	v_ashrrev_i32_e32 v1, 31, v0
	v_lshlrev_b64 v[0:1], 9, v[0:1]
	v_lshl_add_u64 v[0:1], v[0:1], 0, v[72:73]
	v_lshl_add_u64 v[2:3], v[0:1], 2, s[34:35]
	v_lshl_add_u64 v[0:1], v[0:1], 1, s[62:63]
	global_load_dword v78, v[2:3], off
	global_load_ushort v208, v[0:1], off
	v_add_u32_e32 v0, s5, v96
	v_ashrrev_i32_e32 v1, 31, v0
	v_lshlrev_b64 v[0:1], 9, v[0:1]
	v_lshl_add_u64 v[0:1], v[0:1], 0, v[72:73]
	v_lshl_add_u64 v[2:3], v[0:1], 2, s[34:35]
	v_lshl_add_u64 v[0:1], v[0:1], 1, s[62:63]
	global_load_dword v79, v[2:3], off
	global_load_ushort v209, v[0:1], off
	v_add_u32_e32 v0, s5, v97
	v_ashrrev_i32_e32 v1, 31, v0
	v_lshlrev_b64 v[0:1], 9, v[0:1]
	v_lshl_add_u64 v[0:1], v[0:1], 0, v[72:73]
	v_lshl_add_u64 v[2:3], v[0:1], 2, s[34:35]
	v_lshl_add_u64 v[0:1], v[0:1], 1, s[62:63]
	global_load_dword v82, v[2:3], off
	global_load_ushort v210, v[0:1], off
	v_add_u32_e32 v0, s5, v99
	v_ashrrev_i32_e32 v1, 31, v0
	v_lshlrev_b64 v[0:1], 9, v[0:1]
	v_lshl_add_u64 v[0:1], v[0:1], 0, v[72:73]
	v_lshl_add_u64 v[2:3], v[0:1], 2, s[34:35]
	v_lshl_add_u64 v[0:1], v[0:1], 1, s[62:63]
	global_load_dword v83, v[2:3], off
	global_load_ushort v211, v[0:1], off
	v_add_u32_e32 v0, s5, v101
	v_ashrrev_i32_e32 v1, 31, v0
	v_lshlrev_b64 v[0:1], 9, v[0:1]
	v_lshl_add_u64 v[0:1], v[0:1], 0, v[72:73]
	v_lshl_add_u64 v[2:3], v[0:1], 2, s[34:35]
	v_lshl_add_u64 v[0:1], v[0:1], 1, s[62:63]
	global_load_dword v76, v[2:3], off
	global_load_ushort v212, v[0:1], off
	v_add_u32_e32 v0, s5, v103
	v_ashrrev_i32_e32 v1, 31, v0
	v_lshlrev_b64 v[0:1], 9, v[0:1]
	v_lshl_add_u64 v[0:1], v[0:1], 0, v[72:73]
	v_lshl_add_u64 v[2:3], v[0:1], 2, s[34:35]
	v_lshl_add_u64 v[0:1], v[0:1], 1, s[62:63]
	global_load_dword v77, v[2:3], off
	global_load_ushort v213, v[0:1], off
	v_add_u32_e32 v0, s5, v105
	v_ashrrev_i32_e32 v1, 31, v0
	v_lshlrev_b64 v[0:1], 10, v[0:1]
	v_lshl_add_u64 v[0:1], v[80:81], 0, v[0:1]
	global_load_dwordx4 v[0:3], v[0:1], off
	s_bitcmp1_b32 s61, 0
	s_cselect_b32 s74, 0x9600, 0
	v_add_u32_e32 v4, s74, v74
	v_add_u32_e32 v126, v4, v92
	s_waitcnt lgkmcnt(0)
	s_barrier
	ds_read_b128 v[120:123], v126 offset:17408
	v_or_b32_e32 v124, s74, v92
	v_add_u32_e32 v125, v124, v117
	ds_read_b128 v[4:7], v125 offset:27648
	ds_read_b128 v[8:11], v125 offset:28928
	s_waitcnt lgkmcnt(0)
	v_mfma_f32_16x16x32_bf16 v[12:15], v[120:123], v[8:11], v[40:43]
	ds_read_b128 v[8:11], v125 offset:30208
	ds_read_b128 v[28:31], v125 offset:34048
	ds_read_b128 v[32:35], v125 offset:35328
	s_waitcnt lgkmcnt(2)
	v_mfma_f32_16x16x32_bf16 v[16:19], v[120:123], v[8:11], v[44:47]
	ds_read_b128 v[8:11], v125 offset:31488
	s_cmp_gt_u32 s61, 7
	s_mov_b64 s[0:1], -1
	v_mfma_f32_16x16x32_bf16 v[4:7], v[120:123], v[4:7], v[36:39]
	s_waitcnt lgkmcnt(0)
	v_mfma_f32_16x16x32_bf16 v[20:23], v[120:123], v[8:11], v[48:51]
	ds_read_b128 v[8:11], v125 offset:32768
	ds_read_b128 v[36:39], v125 offset:36608
	v_add_u32_e32 v125, v124, v100
	ds_read_b128 v[40:43], v125 offset:8704
	v_add_u32_e32 v124, v124, v112
	ds_read_b128 v[48:51], v124
	v_mfma_f32_16x16x32_bf16 v[28:31], v[120:123], v[28:31], v[56:59]
	s_waitcnt lgkmcnt(2)
	v_mfma_f32_16x16x32_bf16 v[56:59], v[120:123], v[36:39], v[64:67]
	ds_read_b128 v[36:39], v125 offset:8768
	ds_read_b128 v[44:47], v124 offset:64
	v_mfma_f32_16x16x32_bf16 v[8:11], v[120:123], v[8:11], v[52:55]
	s_waitcnt lgkmcnt(2)
	v_mfma_f32_16x16x32_bf16 v[52:55], v[40:43], v[48:51], 0
	v_mfma_f32_16x16x32_bf16 v[32:35], v[120:123], v[32:35], v[60:63]
	s_nop 2
	ds_read_b128 v[60:63], v125 offset:8832
	ds_read_b128 v[40:43], v124 offset:128
	ds_read_b128 v[64:67], v125 offset:13120
	ds_read_b128 v[120:123], v125 offset:13248
	s_waitcnt lgkmcnt(4)
	v_mfma_f32_16x16x32_bf16 v[36:39], v[36:39], v[44:47], v[52:55]
	s_nop 2
	ds_read_b128 v[52:55], v125 offset:8896
	s_waitcnt lgkmcnt(3)
	v_mfma_f32_16x16x32_bf16 v[60:63], v[60:63], v[40:43], v[36:39]
	s_nop 2
	ds_read_b128 v[36:39], v124 offset:192
	s_waitcnt lgkmcnt(0)
	v_mfma_f32_16x16x32_bf16 v[52:55], v[52:55], v[36:39], v[60:63]
	s_nop 2
	ds_read_b128 v[60:63], v125 offset:13056
	s_waitcnt lgkmcnt(0)
	v_mfma_f32_16x16x32_bf16 v[60:63], v[60:63], v[48:51], 0
	v_mfma_f32_16x16x32_bf16 v[60:63], v[64:67], v[44:47], v[60:63]
	ds_read_b128 v[64:67], v125 offset:13184
	s_waitcnt lgkmcnt(0)
	v_mfma_f32_16x16x32_bf16 v[60:63], v[64:67], v[40:43], v[60:63]
	v_add_u32_e32 v64, s74, v113
	ds_read_b128 v[64:67], v64 offset:37888
	v_mfma_f32_16x16x32_bf16 v[60:63], v[120:123], v[36:39], v[60:63]
	s_cbranch_scc0 .LBB0_924
	v_readlane_b32 s0, v251, 15
	s_add_i32 s5, s50, 0xffffff00
	v_readlane_b32 s1, v251, 16
	s_and_b64 s[0:1], s[0:1], exec
	s_cselect_b32 s0, s5, s51
	v_readlane_b32 s1, v254, 36
	s_add_i32 s5, s0, s1
	s_mov_b64 s[0:1], 0

; __device__ __forceinline__ void hgrn_phase(const Params& P, char* shm, int lbid) {
;     ...
;           f32x4 t = __builtin_amdgcn_mfma_f32_16x16x32_bf16(a, bv, Sacc[vt], 0, 0, 0);
;           t[0] *= gl.x; t[1] *= gl.y; t[2] *= gl.z; t[3] *= gl.w;
;           Sacc[vt] = t;
;         }
;       }
;       {
;         const int tt = w >> 2, vt0 = (w & 3) * 2;
;         bf16x8 qf[4];
; #pragma unroll
;         for (int ks = 0; ks < 4; ++ks) qf[ks] = *(const bf16x8*)(pb + PB_Q + (tt * 16 + fr) * QSTR + (ks * 32 + quad * 8) * 2);
;         f32x4 AT[2];
; #pragma unroll
;         for (int st = 0; st < 2; ++st) {
;           f32x4 acc = f32x4{0.f, 0.f, 0.f, 0.f};
; #pragma unroll
;           for (int ks = 0; ks < 4; ++ks) {
;             const bf16x8 kf = *(const bf16x8*)(pb + PB_K + (st * 16 + fr) * QSTR + (ks * 32 + quad * 8) * 2);
;             acc = __builtin_amdgcn_mfma_f32_16x16x32_bf16(kf, qf[ks], acc, 0, 0, 0);
;           }
;           const int tpos = tt * 16 + fr;
; #pragma unroll
;           for (int jj = 0; jj < 4; ++jj)
;             if (st * 16 + quad * 4 + jj > tpos) acc[jj] = 0.0f;
;           AT[st] = acc;
;         }
;         u32x4 ap;
;         ap.x = pack2(AT[0][0], AT[0][1]); ap.y = pack2(AT[0][2], AT[0][3]);
;         ap.z = pack2(AT[1][0], AT[1][1]); ap.w = pack2(AT[1][2], AT[1][3]);
;         const int r0 = HG_R0(c);
; #pragma unroll
;         for (int e = 0; e < 2; ++e) {
;           const int vt = vt0 + e;
;           f32x4 O = f32x4{0.f, 0.f, 0.f, 0.f};
; #pragma unroll
;           for (int ks = 0; ks < 4; ++ks) {
;             const bf16x8 sf = *(const bf16x8*)(sb + (vt * 16 + fr) * QSTR + (ks * 32 + quad * 8) * 2);
;             O = __builtin_amdgcn_mfma_f32_16x16x32_bf16(qf[ks], sf, O, 0, 0, 0);
;           }
;           const char* vp = pb + PB_VT + (vt * 16 + fr) * TSTR + quad * 8;
;           const u32x2 lo = *(const u32x2*)vp, hi = *(const u32x2*)(vp + 32);
;           u32x4 bp; bp.x = lo.x; bp.y = lo.y; bp.z = hi.x; bp.w = hi.y;
;           O = __builtin_amdgcn_mfma_f32_16x16x32_bf16(__builtin_bit_cast(bf16x8, ap), __builtin_bit_cast(bf16x8, bp), O, 0, 0, 0);
; #pragma unroll
;           for (int jj = 0; jj < 4; ++jj)
;             Oo[(size_t)(r0 + sgn * (tt * 16 + quad * 4 + jj)) * 512 + h * 128 + vt * 16 + fr] = O[jj];
;         }
;       }
;       __syncthreads();
.LBB0_926:
	s_nop 0
	s_nop 0
	s_nop 0
	s_nop 0
	s_waitcnt lgkmcnt(0)
	v_pk_mul_f32 v[24:25], v[64:65], v[8:9]
	v_pk_mul_f32 v[8:9], v[64:65], v[56:57]
	v_mov_b32_e32 v56, s75
	v_cndmask_b32_e64 v56, v52, v56, s[16:17]
	v_cndmask_b32_e64 v56, v56, v52, s[14:15]
	v_mov_b32_e32 v52, s75
	s_nop 0
	s_nop 0
	s_nop 0
	s_nop 0
	v_pk_mul_f32 v[26:27], v[66:67], v[10:11]
	v_pk_mul_f32 v[10:11], v[66:67], v[58:59]
	v_cndmask_b32_e64 v53, 0, v53, s[14:15]
	v_cndmask_b32_e64 v54, v54, 0, s[18:19]
	v_cndmask_b32_e64 v55, v55, 0, s[20:21]
	v_cndmask_b32_e64 v57, v60, v52, s[6:7]
	v_cndmask_b32_e64 v58, v61, 0, s[8:9]
	v_cndmask_b32_e64 v59, v62, 0, s[10:11]
	v_cndmask_b32_e64 v60, v63, 0, s[12:13]
	v_cvt_pk_bf16_f32 v52, v56, v53
	v_cvt_pk_bf16_f32 v53, v54, v55
	v_cvt_pk_bf16_f32 v54, v57, v58
	v_cvt_pk_bf16_f32 v55, v59, v60
	ds_read_b128 v[56:59], v75
	ds_read_b128 v[60:63], v75 offset:64
	s_waitcnt lgkmcnt(1)
	v_mfma_f32_16x16x32_bf16 v[56:59], v[48:51], v[56:59], 0
	s_nop 0
	s_nop 0
	s_nop 0
	s_nop 0
	v_add3_u32 v127, s74, v69, v90
	s_waitcnt lgkmcnt(0)
	v_mfma_f32_16x16x32_bf16 v[56:59], v[44:47], v[60:63], v[56:59]
	ds_read_b128 v[60:63], v75 offset:128
	v_pk_mul_f32 v[4:5], v[64:65], v[4:5]
	v_pk_mul_f32 v[12:13], v[64:65], v[12:13]
	s_waitcnt lgkmcnt(0)
	v_mfma_f32_16x16x32_bf16 v[56:59], v[40:43], v[60:63], v[56:59]
	ds_read_b128 v[60:63], v75 offset:192
	v_pk_mul_f32 v[16:17], v[64:65], v[16:17]
	v_pk_mul_f32 v[20:21], v[64:65], v[20:21]
	s_waitcnt lgkmcnt(0)
	v_mfma_f32_16x16x32_bf16 v[56:59], v[36:39], v[60:63], v[56:59]
	v_add_u32_e32 v60, 0x6800, v127
	ds_read2_b64 v[60:63], v60 offset0:128 offset1:132
	v_pk_mul_f32 v[28:29], v[64:65], v[28:29]
	s_waitcnt lgkmcnt(0)
	v_mfma_f32_16x16x32_bf16 v[56:59], v[52:55], v[60:63], v[56:59]
	v_add_u32_e32 v60, s5, v89
	v_ashrrev_i32_e32 v61, 31, v60
	v_add_u32_e32 v62, s5, v88
	v_lshlrev_b64 v[60:61], 11, v[60:61]
	v_ashrrev_i32_e32 v63, 31, v62
	v_lshl_add_u64 v[60:61], v[70:71], 0, v[60:61]
	v_lshlrev_b64 v[62:63], 11, v[62:63]
	s_nop 0
	global_store_dword v[60:61], v56, off
	v_lshl_add_u64 v[62:63], v[70:71], 0, v[62:63]
	v_add_u32_e32 v56, s5, v87
	global_store_dword v[62:63], v57, off
	v_ashrrev_i32_e32 v57, 31, v56
	v_lshlrev_b64 v[56:57], 11, v[56:57]
	v_pk_mul_f32 v[32:33], v[64:65], v[32:33]
	v_lshl_add_u64 v[64:65], v[70:71], 0, v[56:57]
	v_add_u32_e32 v56, s5, v86
	v_ashrrev_i32_e32 v57, 31, v56
	v_lshlrev_b64 v[56:57], 11, v[56:57]
	v_pk_mul_f32 v[6:7], v[66:67], v[6:7]
	v_pk_mul_f32 v[14:15], v[66:67], v[14:15]
	v_pk_mul_f32 v[18:19], v[66:67], v[18:19]
	v_pk_mul_f32 v[22:23], v[66:67], v[22:23]
	v_pk_mul_f32 v[30:31], v[66:67], v[30:31]
	v_pk_mul_f32 v[34:35], v[66:67], v[34:35]
	v_lshl_add_u64 v[66:67], v[70:71], 0, v[56:57]
	global_store_dword v[64:65], v58, off
	global_store_dword v[66:67], v59, off
	ds_read_b128 v[56:59], v75 offset:4352
	s_waitcnt lgkmcnt(0)
	v_mfma_f32_16x16x32_bf16 v[48:51], v[48:51], v[56:59], 0
	ds_read_b128 v[56:59], v75 offset:4416
	s_add_i32 s50, s50, 32
	s_sub_i32 s51, s51, 32
	s_waitcnt lgkmcnt(0)
	v_mfma_f32_16x16x32_bf16 v[44:47], v[44:47], v[56:59], v[48:51]
	s_nop 0
	s_nop 1
	ds_read_b128 v[48:51], v75 offset:4480
	s_nop 0
	s_nop 0
	s_waitcnt lgkmcnt(0)
	v_mfma_f32_16x16x32_bf16 v[40:43], v[40:43], v[48:51], v[44:47]
	s_nop 2
	ds_read_b128 v[44:47], v75 offset:4544
	s_cmpk_eq_i32 s50, 0x8c0
	s_waitcnt lgkmcnt(0)
	v_mfma_f32_16x16x32_bf16 v[36:39], v[36:39], v[44:47], v[40:43]
	s_nop 2
	v_add_u32_e32 v40, 0x7000, v127
	ds_read2_b64 v[40:43], v40 offset0:32 offset1:36
	s_waitcnt lgkmcnt(0)
	v_mfma_f32_16x16x32_bf16 v[36:39], v[52:55], v[40:43], v[36:39]
	s_nop 7
	global_store_dword v[60:61], v36, off offset:64
	global_store_dword v[62:63], v37, off offset:64
	global_store_dword v[64:65], v38, off offset:64
	global_store_dword v[66:67], v39, off offset:64
	s_barrier
	s_waitcnt vmcnt(9)
	v_mov_b32_e32 v125, v206
	v_mov_b32_e32 v124, v207
	v_mov_b32_e32 v123, v208
	v_mov_b32_e32 v121, v209
	v_mov_b32_e32 v120, v211
	v_mov_b32_e32 v119, v212
	v_mov_b32_e32 v122, v210
	v_mov_b32_e32 v118, v213
	s_cbranch_scc1 .LBB0_928
	s_mov_b32 s61, s4
	v_mov_b32_e32 v36, v4
	v_mov_b32_e32 v37, v5
	v_mov_b32_e32 v38, v6
	v_mov_b32_e32 v39, v7
	v_mov_b32_e32 v40, v12
	v_mov_b32_e32 v41, v13
	v_mov_b32_e32 v42, v14
	v_mov_b32_e32 v43, v15
	v_mov_b32_e32 v44, v16
	v_mov_b32_e32 v45, v17
	v_mov_b32_e32 v46, v18
	v_mov_b32_e32 v47, v19
	v_mov_b32_e32 v48, v20
	v_mov_b32_e32 v49, v21
	v_mov_b32_e32 v50, v22
	v_mov_b32_e32 v51, v23
	v_mov_b32_e32 v52, v24
	v_mov_b32_e32 v53, v25
	v_mov_b32_e32 v54, v26
	v_mov_b32_e32 v55, v27
	v_mov_b32_e32 v56, v28
	v_mov_b32_e32 v57, v29
	v_mov_b32_e32 v58, v30
	v_mov_b32_e32 v59, v31
	v_mov_b32_e32 v60, v32
	v_mov_b32_e32 v61, v33
	v_mov_b32_e32 v62, v34
	v_mov_b32_e32 v63, v35
	v_mov_b32_e32 v64, v8
	v_mov_b32_e32 v65, v9
	v_mov_b32_e32 v66, v10
	v_mov_b32_e32 v67, v11
	s_branch .LBB0_908
